# pass C: batched final-loop loads; MFMA section re-emitted with LDS fragment reads two K-slices ahead
# baseline (speedup 1.0000x reference)
.LBB0_715:
	s_or_b64 exec, exec, s[0:1]
	s_lshl_b32 s78, s96, 7
	ds_write_b16 v119, v34 offset:44048
	v_lshl_add_u32 v48, s78, 2, v95
	ds_read_b32 v48, v48
	s_lshl_b32 s0, s96, 6
	s_mov_b64 s[94:95], 0
	s_waitcnt vmcnt(4)
	v_lshlrev_b32_e32 v44, 16, v236
	v_and_b32_e32 v32, 0xffff0000, v236
	s_waitcnt lgkmcnt(0)
	v_mul_f32_e32 v32, v48, v32
	s_waitcnt vmcnt(3)
	v_lshlrev_b32_e32 v41, 16, v241
	v_cvt_pk_bf16_f32 v32, v32, s0
	ds_write_b16 v102, v32 offset:2176
	v_mul_f32_e32 v32, v48, v41
	v_lshlrev_b32_e32 v45, 16, v237
	v_cvt_pk_bf16_f32 v32, v32, s0
	ds_write_b16 v100, v32 offset:544
	v_mul_f32_e32 v32, v48, v45
	v_and_b32_e32 v37, 0xffff0000, v241
	v_cvt_pk_bf16_f32 v32, v32, s0
	ds_write_b16 v103, v32 offset:2176
	v_mul_f32_e32 v32, v48, v37
	v_and_b32_e32 v33, 0xffff0000, v237
	v_cvt_pk_bf16_f32 v32, v32, s0
	ds_write_b16 v100, v32 offset:816
	v_mul_f32_e32 v32, v48, v33
	v_lshlrev_b32_e32 v42, 16, v242
	v_cvt_pk_bf16_f32 v32, v32, s0
	ds_write_b16 v104, v32 offset:2176
	v_mul_f32_e32 v32, v48, v42
	v_lshlrev_b32_e32 v46, 16, v238
	v_cvt_pk_bf16_f32 v32, v32, s0
	ds_write_b16 v100, v32 offset:1088
	v_mul_f32_e32 v32, v48, v46
	v_and_b32_e32 v38, 0xffff0000, v242
	v_cvt_pk_bf16_f32 v32, v32, s0
	ds_write_b16 v105, v32 offset:2176
	v_mul_f32_e32 v32, v48, v38
	v_and_b32_e32 v34, 0xffff0000, v238
	v_cvt_pk_bf16_f32 v32, v32, s0
	ds_write_b16 v100, v32 offset:1360
	v_mul_f32_e32 v32, v48, v34
	v_lshlrev_b32_e32 v43, 16, v243
	v_cvt_pk_bf16_f32 v32, v32, s0
	ds_write_b16 v106, v32 offset:2176
	v_mul_f32_e32 v32, v48, v43
	v_lshlrev_b32_e32 v47, 16, v239
	v_cvt_pk_bf16_f32 v32, v32, s0
	ds_write_b16 v100, v32 offset:1632
	v_mul_f32_e32 v32, v48, v47
	v_and_b32_e32 v39, 0xffff0000, v243
	v_cvt_pk_bf16_f32 v32, v32, s0
	v_lshlrev_b32_e32 v40, 16, v240
	ds_write_b16 v107, v32 offset:2176
	v_mul_f32_e32 v32, v48, v39
	v_and_b32_e32 v35, 0xffff0000, v239
	v_mul_f32_e32 v40, v48, v40
	v_cvt_pk_bf16_f32 v32, v32, s0
	v_and_b32_e32 v36, 0xffff0000, v240
	v_cvt_pk_bf16_f32 v40, v40, s0
	ds_write_b16 v100, v32 offset:1904
	v_mul_f32_e32 v32, v48, v35
	ds_write_b16 v100, v40
	v_mul_f32_e32 v40, v48, v44
	v_mul_f32_e32 v36, v48, v36
	v_cvt_pk_bf16_f32 v32, v32, s0
	v_cvt_pk_bf16_f32 v40, v40, s0
	v_cvt_pk_bf16_f32 v36, v36, s0
	ds_write_b16 v108, v32 offset:2176
	ds_write_b16 v101, v40 offset:2176
	ds_write_b16 v100, v36 offset:272
	s_waitcnt vmcnt(1)
	ds_write_b128 v114, v[244:247]
	ds_write_b128 v114, v[248:251] offset:8704
	v_add_lshl_u32 v253, s0, v71, 1
	v_add_co_u32_e32 v254, vcc, v76, v253
	s_nop 1
	v_addc_co_u32_e32 v255, vcc, 0, v77, vcc
	global_load_dwordx2 v[236:237], v[254:255], off
	global_load_dwordx2 v[238:239], v[254:255], off offset:32
	global_load_dwordx2 v[240:241], v[254:255], off offset:64
	global_load_dwordx2 v[242:243], v[254:255], off offset:96
	v_add_co_u32_e32 v254, vcc, v74, v253
	s_nop 1
	v_addc_co_u32_e32 v255, vcc, 0, v75, vcc
	global_load_dwordx2 v[244:245], v[254:255], off
	global_load_dwordx2 v[246:247], v[254:255], off offset:32
	global_load_dwordx2 v[248:249], v[254:255], off offset:64
	global_load_dwordx2 v[250:251], v[254:255], off offset:96
	s_waitcnt lgkmcnt(0)
	s_barrier
	v_lshl_add_u32 v64, s78, 2, v98
	ds_read_b32 v64, v64 offset:4096
	ds_read_b128 v[186:189], v91 offset:43008
	ds_read_b128 v[190:193], v96
	ds_read_b128 v[194:197], v96 offset:4352
	ds_read_b128 v[198:201], v96 offset:8704
	ds_read_b128 v[202:205], v96 offset:13056
	ds_read_b128 v[206:209], v91 offset:43072
	ds_read_b128 v[210:213], v96 offset:64
	ds_read_b128 v[214:217], v96 offset:4416
	ds_read_b128 v[218:221], v96 offset:8768
	ds_read_b128 v[222:225], v96 offset:13120
	s_add_i32 s94, s96, s68
	s_mov_b32 s95, s79
	s_lshl_b64 vcc, s[94:95], 2
	v_readlane_b32 s80, v235, 23
	v_readlane_b32 s94, v235, 37
	v_readlane_b32 s81, v235, 24
	v_readlane_b32 s95, v235, 38
	s_add_u32 s94, s80, vcc_lo
	s_addc_u32 s95, s81, vcc_hi
	s_add_i32 s96, s96, 1
	s_cmp_eq_u32 s96, 8
	v_readlane_b32 s82, v235, 25
	v_readlane_b32 s83, v235, 26
	v_readlane_b32 s84, v235, 27
	v_readlane_b32 s85, v235, 28
	v_readlane_b32 s86, v235, 29
	v_readlane_b32 s87, v235, 30
	v_readlane_b32 s88, v235, 31
	v_readlane_b32 s89, v235, 32
	v_readlane_b32 s90, v235, 33
	v_readlane_b32 s91, v235, 34
	v_readlane_b32 s92, v235, 35
	v_readlane_b32 s93, v235, 36
	s_waitcnt lgkmcnt(5)
	v_mfma_f32_16x16x32_bf16 v[56:59], v[190:193], v[186:189], 0
	v_mfma_f32_16x16x32_bf16 v[48:51], v[194:197], v[186:189], 0
	v_mfma_f32_16x16x32_bf16 v[40:43], v[198:201], v[186:189], 0
	v_mfma_f32_16x16x32_bf16 v[32:35], v[202:205], v[186:189], 0
	ds_read_b128 v[186:189], v91 offset:43136
	ds_read_b128 v[190:193], v96 offset:128
	ds_read_b128 v[194:197], v96 offset:4480
	ds_read_b128 v[198:201], v96 offset:8832
	ds_read_b128 v[202:205], v96 offset:13184
	v_mul_f32_e32 v64, 0x3fb8aa3b, v64
	v_exp_f32_e32 v82, v64
	v_add_lshl_u32 v64, s0, v71, 1
	s_waitcnt lgkmcnt(5)
	v_mfma_f32_16x16x32_bf16 v[56:59], v[210:213], v[206:209], v[56:59]
	v_mfma_f32_16x16x32_bf16 v[48:51], v[214:217], v[206:209], v[48:51]
	v_mfma_f32_16x16x32_bf16 v[40:43], v[218:221], v[206:209], v[40:43]
	v_mfma_f32_16x16x32_bf16 v[32:35], v[222:225], v[206:209], v[32:35]
	ds_read_b128 v[206:209], v91 offset:43200
	ds_read_b128 v[210:213], v96 offset:192
	ds_read_b128 v[214:217], v96 offset:4544
	ds_read_b128 v[218:221], v96 offset:8896
	ds_read_b128 v[222:225], v96 offset:13248
	s_waitcnt lgkmcnt(5)
	v_mfma_f32_16x16x32_bf16 v[56:59], v[190:193], v[186:189], v[56:59]
	v_mfma_f32_16x16x32_bf16 v[48:51], v[194:197], v[186:189], v[48:51]
	v_mfma_f32_16x16x32_bf16 v[40:43], v[198:201], v[186:189], v[40:43]
	v_mfma_f32_16x16x32_bf16 v[32:35], v[202:205], v[186:189], v[32:35]
	ds_read_b128 v[186:189], v91 offset:8192
	ds_read_b128 v[190:193], v97
	ds_read_b128 v[194:197], v97 offset:4352
	ds_read_b128 v[198:201], v97 offset:8704
	ds_read_b128 v[202:205], v97 offset:13056
	s_waitcnt lgkmcnt(5)
	v_mfma_f32_16x16x32_bf16 v[56:59], v[210:213], v[206:209], v[56:59]
	v_mfma_f32_16x16x32_bf16 v[48:51], v[214:217], v[206:209], v[48:51]
	v_mfma_f32_16x16x32_bf16 v[40:43], v[218:221], v[206:209], v[40:43]
	v_mfma_f32_16x16x32_bf16 v[32:35], v[222:225], v[206:209], v[32:35]
	ds_read_b128 v[206:209], v91 offset:8256
	ds_read_b128 v[210:213], v97 offset:64
	ds_read_b128 v[214:217], v97 offset:4416
	ds_read_b128 v[218:221], v97 offset:8768
	ds_read_b128 v[222:225], v97 offset:13120
	s_waitcnt lgkmcnt(5)
	v_mfma_f32_16x16x32_bf16 v[60:63], v[190:193], v[186:189], 0
	v_mfma_f32_16x16x32_bf16 v[52:55], v[194:197], v[186:189], 0
	v_mfma_f32_16x16x32_bf16 v[44:47], v[198:201], v[186:189], 0
	v_mfma_f32_16x16x32_bf16 v[36:39], v[202:205], v[186:189], 0
	ds_read_b128 v[186:189], v91 offset:8320
	ds_read_b128 v[190:193], v97 offset:128
	ds_read_b128 v[194:197], v97 offset:4480
	ds_read_b128 v[198:201], v97 offset:8832
	ds_read_b128 v[202:205], v97 offset:13184
	s_waitcnt lgkmcnt(5)
	v_mfma_f32_16x16x32_bf16 v[60:63], v[210:213], v[206:209], v[60:63]
	v_mfma_f32_16x16x32_bf16 v[52:55], v[214:217], v[206:209], v[52:55]
	v_mfma_f32_16x16x32_bf16 v[44:47], v[218:221], v[206:209], v[44:47]
	v_mfma_f32_16x16x32_bf16 v[36:39], v[222:225], v[206:209], v[36:39]
	ds_read_b128 v[206:209], v91 offset:8384
	ds_read_b128 v[210:213], v97 offset:192
	ds_read_b128 v[214:217], v97 offset:4544
	ds_read_b128 v[218:221], v97 offset:8896
	ds_read_b128 v[222:225], v97 offset:13248
	s_waitcnt lgkmcnt(5)
	v_mfma_f32_16x16x32_bf16 v[60:63], v[190:193], v[186:189], v[60:63]
	v_mfma_f32_16x16x32_bf16 v[52:55], v[194:197], v[186:189], v[52:55]
	v_mfma_f32_16x16x32_bf16 v[44:47], v[198:201], v[186:189], v[44:47]
	v_mfma_f32_16x16x32_bf16 v[36:39], v[202:205], v[186:189], v[36:39]
	s_waitcnt lgkmcnt(0)
	v_mfma_f32_16x16x32_bf16 v[60:63], v[210:213], v[206:209], v[60:63]
	v_mfma_f32_16x16x32_bf16 v[52:55], v[214:217], v[206:209], v[52:55]
	v_mfma_f32_16x16x32_bf16 v[44:47], v[218:221], v[206:209], v[44:47]
	v_mfma_f32_16x16x32_bf16 v[36:39], v[222:225], v[206:209], v[36:39]
	s_nop 7
	s_nop 1
	v_pk_fma_f32 v[56:57], v[60:61], v[82:83], v[56:57] op_sel_hi:[1,0,1]
	v_pk_fma_f32 v[58:59], v[62:63], v[82:83], v[58:59] op_sel_hi:[1,0,1]
	v_pk_fma_f32 v[48:49], v[52:53], v[82:83], v[48:49] op_sel_hi:[1,0,1]
	v_pk_fma_f32 v[50:51], v[54:55], v[82:83], v[50:51] op_sel_hi:[1,0,1]
	v_pk_fma_f32 v[40:41], v[44:45], v[82:83], v[40:41] op_sel_hi:[1,0,1]
	v_pk_fma_f32 v[42:43], v[46:47], v[82:83], v[42:43] op_sel_hi:[1,0,1]
	v_pk_fma_f32 v[32:33], v[36:37], v[82:83], v[32:33] op_sel_hi:[1,0,1]
	v_pk_fma_f32 v[34:35], v[38:39], v[82:83], v[34:35] op_sel_hi:[1,0,1]
	s_mov_b64 s[0:1], 0x4000
	v_lshl_add_u64 v[80:81], v[80:81], 0, s[0:1]
	s_waitcnt vmcnt(7)
	v_lshlrev_b32_e32 v128, 16, v236
	v_and_b32_e32 v129, 0xffff0000, v236
	s_waitcnt vmcnt(3)
	v_lshlrev_b32_e32 v126, 16, v244
	v_and_b32_e32 v127, 0xffff0000, v244
	v_mul_f32_e32 v122, 0xbfb8aa3b, v128
	v_mul_f32_e32 v60, 0xbfb8aa3b, v129
	v_exp_f32_e32 v122, v122
	v_exp_f32_e32 v60, v60
	v_pk_fma_f32 v[56:57], v[252:253], v[126:127], v[56:57] op_sel_hi:[0,1,1]
	v_add_f32_e32 v122, 1.0, v122
	v_add_f32_e32 v60, 1.0, v60
	v_rcp_f32_e32 v130, v122
	v_rcp_f32_e32 v131, v60
	v_lshlrev_b32_e32 v122, 16, v237
	v_pk_mul_f32 v[60:61], v[130:131], v[128:129]
	s_nop 0
	v_pk_mul_f32 v[56:57], v[56:57], v[60:61]
	s_nop 0
	v_pk_mul_f32 v[60:61], v[56:57], v[56:57]
	s_nop 0
	v_add_f32_e32 v60, v121, v60
	v_add_f32_e32 v61, v61, v60
	v_cvt_pk_bf16_f32 v60, v56, v57
	v_lshlrev_b32_e32 v56, 16, v245
	v_and_b32_e32 v57, 0xffff0000, v245
	v_and_b32_e32 v123, 0xffff0000, v237
	v_mul_f32_e32 v121, 0xbfb8aa3b, v122
	v_pk_fma_f32 v[56:57], v[252:253], v[56:57], v[58:59] op_sel_hi:[0,1,1]
	v_mul_f32_e32 v58, 0xbfb8aa3b, v123
	v_exp_f32_e32 v121, v121
	v_exp_f32_e32 v58, v58
	v_add_f32_e32 v121, 1.0, v121
	v_add_f32_e32 v58, 1.0, v58
	v_rcp_f32_e32 v124, v121
	v_rcp_f32_e32 v125, v58
	s_nop 0
	v_pk_mul_f32 v[58:59], v[124:125], v[122:123]
	s_nop 0
	v_pk_mul_f32 v[56:57], v[56:57], v[58:59]
	s_nop 0
	v_pk_mul_f32 v[58:59], v[56:57], v[56:57]
	s_nop 0
	v_add_f32_e32 v58, v58, v61
	v_cvt_pk_bf16_f32 v61, v56, v57
	v_lshl_add_u64 v[56:57], v[78:79], 0, v[64:65]
	global_store_dwordx2 v[56:57], v[60:61], off
	v_add_f32_e32 v121, v59, v58
	s_waitcnt vmcnt(3)
	v_lshlrev_b32_e32 v62, 16, v246
	s_waitcnt vmcnt(7)
	v_lshlrev_b32_e32 v122, 16, v238
	v_and_b32_e32 v123, 0xffff0000, v238
	v_and_b32_e32 v63, 0xffff0000, v246
	v_mul_f32_e32 v58, 0xbfb8aa3b, v122
	v_mul_f32_e32 v52, 0xbfb8aa3b, v123
	v_exp_f32_e32 v58, v58
	v_exp_f32_e32 v52, v52
	v_pk_fma_f32 v[48:49], v[252:253], v[62:63], v[48:49] op_sel_hi:[0,1,1]
	v_add_f32_e32 v58, 1.0, v58
	v_add_f32_e32 v52, 1.0, v52
	v_rcp_f32_e32 v124, v58
	v_rcp_f32_e32 v125, v52
	v_lshlrev_b32_e32 v58, 16, v239
	v_pk_mul_f32 v[52:53], v[124:125], v[122:123]
	s_nop 0
	v_pk_mul_f32 v[48:49], v[48:49], v[52:53]
	s_nop 0
	v_pk_mul_f32 v[52:53], v[48:49], v[48:49]
	v_cvt_pk_bf16_f32 v48, v48, v49
	v_mul_f32_e32 v49, 0xbfb8aa3b, v58
	v_exp_f32_e32 v49, v49
	v_add_f32_e32 v52, v52, v121
	v_add_f32_e32 v62, v53, v52
	v_lshlrev_b32_e32 v52, 16, v247
	v_and_b32_e32 v53, 0xffff0000, v247
	v_and_b32_e32 v59, 0xffff0000, v239
	v_add_f32_e32 v49, 1.0, v49
	v_rcp_f32_e32 v60, v49
	v_mul_f32_e32 v49, 0xbfb8aa3b, v59
	v_exp_f32_e32 v49, v49
	v_pk_fma_f32 v[50:51], v[252:253], v[52:53], v[50:51] op_sel_hi:[0,1,1]
	v_add_f32_e32 v49, 1.0, v49
	v_rcp_f32_e32 v61, v49
	s_nop 0
	v_pk_mul_f32 v[52:53], v[60:61], v[58:59]
	s_nop 0
	v_pk_mul_f32 v[50:51], v[50:51], v[52:53]
	s_nop 0
	v_pk_mul_f32 v[52:53], v[50:51], v[50:51]
	s_nop 0
	v_add_f32_e32 v49, v52, v62
	v_add_f32_e32 v60, v53, v49
	v_cvt_pk_bf16_f32 v49, v50, v51
	global_store_dwordx2 v[56:57], v[48:49], off offset:32
	s_waitcnt vmcnt(3)
	v_lshlrev_b32_e32 v52, 16, v248
	s_waitcnt vmcnt(7)
	v_lshlrev_b32_e32 v54, 16, v240
	v_and_b32_e32 v55, 0xffff0000, v240
	v_and_b32_e32 v53, 0xffff0000, v248
	v_mul_f32_e32 v48, 0xbfb8aa3b, v54
	v_mul_f32_e32 v44, 0xbfb8aa3b, v55
	v_exp_f32_e32 v48, v48
	v_exp_f32_e32 v44, v44
	v_pk_fma_f32 v[40:41], v[252:253], v[52:53], v[40:41] op_sel_hi:[0,1,1]
	v_add_f32_e32 v48, 1.0, v48
	v_add_f32_e32 v44, 1.0, v44
	v_rcp_f32_e32 v58, v48
	v_rcp_f32_e32 v59, v44
	v_lshlrev_b32_e32 v48, 16, v241
	v_pk_mul_f32 v[44:45], v[58:59], v[54:55]
	s_nop 0
	v_pk_mul_f32 v[40:41], v[40:41], v[44:45]
	s_nop 0
	v_pk_mul_f32 v[44:45], v[40:41], v[40:41]
	v_cvt_pk_bf16_f32 v40, v40, v41
	v_mul_f32_e32 v41, 0xbfb8aa3b, v48
	v_exp_f32_e32 v41, v41
	v_add_f32_e32 v44, v44, v60
	v_add_f32_e32 v52, v45, v44
	v_lshlrev_b32_e32 v44, 16, v249
	v_and_b32_e32 v45, 0xffff0000, v249
	v_and_b32_e32 v49, 0xffff0000, v241
	v_add_f32_e32 v41, 1.0, v41
	v_rcp_f32_e32 v50, v41
	v_mul_f32_e32 v41, 0xbfb8aa3b, v49
	v_exp_f32_e32 v41, v41
	v_pk_fma_f32 v[42:43], v[252:253], v[44:45], v[42:43] op_sel_hi:[0,1,1]
	v_add_f32_e32 v41, 1.0, v41
	v_rcp_f32_e32 v51, v41
	s_nop 0
	v_pk_mul_f32 v[44:45], v[50:51], v[48:49]
	s_nop 0
	v_pk_mul_f32 v[42:43], v[42:43], v[44:45]
	s_nop 0
	v_pk_mul_f32 v[44:45], v[42:43], v[42:43]
	s_nop 0
	v_add_f32_e32 v41, v44, v52
	v_add_f32_e32 v50, v45, v41
	v_cvt_pk_bf16_f32 v41, v42, v43
	global_store_dwordx2 v[56:57], v[40:41], off offset:64
	s_waitcnt vmcnt(3)
	v_lshlrev_b32_e32 v44, 16, v250
	s_waitcnt vmcnt(7)
	v_lshlrev_b32_e32 v46, 16, v242
	v_and_b32_e32 v47, 0xffff0000, v242
	v_and_b32_e32 v45, 0xffff0000, v250
	v_mul_f32_e32 v40, 0xbfb8aa3b, v46
	v_mul_f32_e32 v36, 0xbfb8aa3b, v47
	v_exp_f32_e32 v40, v40
	v_exp_f32_e32 v36, v36
	v_pk_fma_f32 v[32:33], v[252:253], v[44:45], v[32:33] op_sel_hi:[0,1,1]
	v_add_f32_e32 v40, 1.0, v40
	v_add_f32_e32 v36, 1.0, v36
	v_rcp_f32_e32 v48, v40
	v_rcp_f32_e32 v49, v36
	v_lshlrev_b32_e32 v40, 16, v243
	v_pk_mul_f32 v[36:37], v[48:49], v[46:47]
	s_nop 0
	v_pk_mul_f32 v[32:33], v[32:33], v[36:37]
	s_nop 0
	v_pk_mul_f32 v[36:37], v[32:33], v[32:33]
	v_cvt_pk_bf16_f32 v32, v32, v33
	v_mul_f32_e32 v33, 0xbfb8aa3b, v40
	v_exp_f32_e32 v33, v33
	v_add_f32_e32 v36, v36, v50
	v_add_f32_e32 v44, v37, v36
	v_lshlrev_b32_e32 v36, 16, v251
	v_and_b32_e32 v37, 0xffff0000, v251
	v_and_b32_e32 v41, 0xffff0000, v243
	v_add_f32_e32 v33, 1.0, v33
	v_rcp_f32_e32 v42, v33
	v_mul_f32_e32 v33, 0xbfb8aa3b, v41
	v_exp_f32_e32 v33, v33
	v_pk_fma_f32 v[34:35], v[252:253], v[36:37], v[34:35] op_sel_hi:[0,1,1]
	v_add_f32_e32 v33, 1.0, v33
	v_rcp_f32_e32 v43, v33
	s_nop 0
	v_pk_mul_f32 v[36:37], v[42:43], v[40:41]
	s_nop 0
	v_pk_mul_f32 v[34:35], v[34:35], v[36:37]
	s_nop 0
	v_pk_mul_f32 v[36:37], v[34:35], v[34:35]
	s_nop 0
	v_add_f32_e32 v33, v36, v44
	v_add_f32_e32 v121, v37, v33
	v_cvt_pk_bf16_f32 v33, v34, v35
	global_store_dwordx2 v[56:57], v[32:33], off offset:96
	s_barrier
	s_cbranch_scc0 .LBB0_651
	ds_bpermute_b32 v0, v109, v121
	v_lshl_or_b32 v4, v120, 9, v93
	v_readlane_b32 s0, v234, 23
	v_lshlrev_b32_e32 v64, 2, v4
	v_readlane_b32 s1, v234, 24
	s_waitcnt lgkmcnt(0)
	v_add_f32_e32 v5, v121, v0
	ds_bpermute_b32 v6, v110, v5
	v_lshl_add_u64 v[0:1], s[0:1], 0, v[64:65]
	s_mov_b32 s0, 0x800000
	v_add_u32_e32 v2, s73, v92
	v_ashrrev_i32_e32 v3, 31, v2
	s_waitcnt lgkmcnt(0)
	v_add_f32_e32 v5, v5, v6
	v_fmamk_f32 v5, v5, 0x3b000000, v118
	v_mul_f32_e32 v6, 0x4b800000, v5
	v_cmp_gt_f32_e32 vcc, s0, v5
	v_lshlrev_b64 v[2:3], 12, v[2:3]
	v_lshl_or_b32 v2, v4, 1, v2
	v_cndmask_b32_e32 v5, v5, v6, vcc
	v_rsq_f32_e32 v5, v5
	v_readlane_b32 s84, v234, 11
	v_readlane_b32 s86, v234, 13
	v_readlane_b32 s87, v234, 14
	v_mul_f32_e32 v4, 0x45800000, v5
	v_cndmask_b32_e32 v4, v5, v4, vcc
	v_lshl_add_u64 v[2:3], s[86:87], 0, v[2:3]
	v_mov_b32_e32 v5, v4
	s_mov_b64 s[94:95], 0
	v_readlane_b32 s85, v234, 12
.LBB0_719:
	v_lshl_add_u64 v[6:7], v[2:3], 0, s[94:95]
	v_add_co_u32_e32 v6, vcc, 0x9000000, v6
	s_add_u32 s94, s94, 0x80
	s_nop 0
	v_addc_co_u32_e32 v7, vcc, 0, v7, vcc
	global_load_dwordx2 v[236:237], v[6:7], off
	global_load_dwordx4 v[8:11], v[0:1], off offset:-128
	global_load_dwordx2 v[238:239], v[6:7], off offset:32
	global_load_dwordx4 v[244:247], v[0:1], off offset:-64
	global_load_dwordx2 v[240:241], v[6:7], off offset:64
	global_load_dwordx4 v[248:251], v[0:1], off
	global_load_dwordx2 v[242:243], v[6:7], off offset:96
	global_load_dwordx4 v[252:255], v[0:1], off offset:64
	s_addc_u32 s95, s95, 0
	s_mov_b64 s[0:1], 0x100
	s_cmpk_lg_i32 s94, 0x400
	s_waitcnt vmcnt(7)
	v_lshlrev_b32_e32 v14, 16, v236
	v_and_b32_e32 v15, 0xffff0000, v236
	v_lshlrev_b32_e32 v12, 16, v237
	v_and_b32_e32 v13, 0xffff0000, v237
	v_pk_mul_f32 v[14:15], v[4:5], v[14:15]
	v_pk_mul_f32 v[12:13], v[4:5], v[12:13]
	s_waitcnt vmcnt(6)
	v_pk_mul_f32 v[8:9], v[8:9], v[14:15]
	v_pk_mul_f32 v[10:11], v[10:11], v[12:13]
	v_cvt_pk_bf16_f32 v8, v8, v9
	v_cvt_pk_bf16_f32 v9, v10, v11
	global_store_dwordx2 v[6:7], v[8:9], off
	s_waitcnt vmcnt(6)
	v_lshlrev_b32_e32 v14, 16, v238
	v_and_b32_e32 v15, 0xffff0000, v238
	v_lshlrev_b32_e32 v12, 16, v239
	v_and_b32_e32 v13, 0xffff0000, v239
	v_pk_mul_f32 v[14:15], v[4:5], v[14:15]
	v_pk_mul_f32 v[12:13], v[4:5], v[12:13]
	s_waitcnt vmcnt(5)
	v_pk_mul_f32 v[8:9], v[244:245], v[14:15]
	v_pk_mul_f32 v[10:11], v[246:247], v[12:13]
	v_cvt_pk_bf16_f32 v8, v8, v9
	v_cvt_pk_bf16_f32 v9, v10, v11
	global_store_dwordx2 v[6:7], v[8:9], off offset:32
	s_waitcnt vmcnt(5)
	v_lshlrev_b32_e32 v14, 16, v240
	v_and_b32_e32 v15, 0xffff0000, v240
	v_lshlrev_b32_e32 v12, 16, v241
	v_and_b32_e32 v13, 0xffff0000, v241
	v_pk_mul_f32 v[14:15], v[4:5], v[14:15]
	v_pk_mul_f32 v[12:13], v[4:5], v[12:13]
	s_waitcnt vmcnt(4)
	v_pk_mul_f32 v[8:9], v[248:249], v[14:15]
	v_pk_mul_f32 v[10:11], v[250:251], v[12:13]
	v_cvt_pk_bf16_f32 v8, v8, v9
	v_cvt_pk_bf16_f32 v9, v10, v11
	global_store_dwordx2 v[6:7], v[8:9], off offset:64
	v_lshl_add_u64 v[0:1], v[0:1], 0, s[0:1]
	s_waitcnt vmcnt(4)
	v_lshlrev_b32_e32 v14, 16, v242
	v_and_b32_e32 v15, 0xffff0000, v242
	v_lshlrev_b32_e32 v12, 16, v243
	v_and_b32_e32 v13, 0xffff0000, v243
	v_pk_mul_f32 v[14:15], v[4:5], v[14:15]
	v_pk_mul_f32 v[12:13], v[4:5], v[12:13]
	s_waitcnt vmcnt(3)
	v_pk_mul_f32 v[8:9], v[252:253], v[14:15]
	v_pk_mul_f32 v[10:11], v[254:255], v[12:13]
	v_cvt_pk_bf16_f32 v8, v8, v9
	v_cvt_pk_bf16_f32 v9, v10, v11
	global_store_dwordx2 v[6:7], v[8:9], off offset:96
	s_cbranch_scc1 .LBB0_719
	v_readlane_b32 s0, v234, 21
	s_mov_b64 s[96:97], s[76:77]
	v_readlane_b32 s1, v234, 22
	s_add_i32 s33, s33, s96
	s_xor_b64 s[70:71], s[70:71], s[0:1]
	s_cmpk_lt_i32 s33, 0x100
	s_barrier
	s_cbranch_scc1 .LBB0_646
	v_readlane_b32 s64, v234, 11
	v_readlane_b32 s66, v234, 13
	v_readlane_b32 s67, v234, 14
	s_add_u32 s10, s66, 0x19000000
	s_addc_u32 s11, s67, 0
	s_add_u32 s12, s66, 0x1b000000
	s_addc_u32 s13, s67, 0
	v_readlane_b32 s65, v234, 12
	s_add_u32 s14, s64, 0x5200000
	s_movk_i32 s0, 0x100
	s_addc_u32 s15, s65, 0
	v_cmp_gt_u32_e64 s[2:3], s0, v170
	s_add_i32 s0, 0, 0x18200
	s_add_i32 s1, 0, 0x14000
	s_add_i32 s4, 0, 0x19200
	s_lshl_b32 s33, s96, 2
	s_add_u32 s18, s66, 0x6000000
	s_addc_u32 s19, s67, 0
	v_lshrrev_b32_e32 v0, 6, v170
	v_and_b32_e32 v1, 12, v83
	s_add_u32 s20, s66, 0x4000000
	v_lshl_or_b32 v1, v0, 4, v1
	s_addc_u32 s21, s67, 0
	v_add_u32_e32 v39, s0, v1
	v_add_u32_e32 v41, s1, v1
	v_add_u32_e32 v3, 0xffffff00, v170
	v_add_u32_e32 v0, -4, v0
	s_movk_i32 s5, 0x2100
	v_mov_b32_e32 v1, s4
	s_add_u32 s22, s66, 0x3800000
	v_lshrrev_b32_e32 v34, 4, v3
	v_mad_i32_i24 v4, v0, s5, v1
	v_cmp_lt_u32_e64 s[4:5], 15, v3
	v_bfe_u32 v139, v170, 3, 3
	v_and_b32_e32 v42, 56, v99
	v_lshrrev_b32_e32 v44, 3, v3
	v_lshlrev_b32_e32 v3, 1, v170
	s_addc_u32 s23, s67, 0
	v_lshl_add_u32 v47, s69, 2, v0
	v_mul_u32_u24_e32 v0, 0x84, v42
	v_lshlrev_b32_e32 v5, 2, v139
	v_and_b32_e32 v46, 14, v3
	s_add_u32 s24, s66, 0x2000000
	v_add3_u32 v140, v4, v0, v5
	v_lshlrev_b32_e32 v0, 6, v44
	v_lshlrev_b32_e32 v3, 2, v46
	s_addc_u32 s25, s67, 0
	v_mov_b32_e32 v1, 0
	v_add3_u32 v144, s0, v0, v3
	s_movk_i32 s0, 0x500
	s_add_u32 s26, s66, 0x1800000
	v_mul_u32_u24_e32 v2, 20, v67
	v_mov_b32_e32 v35, v1
	v_add_u32_e32 v36, 16, v34
	v_lshl_add_u32 v136, v67, 4, s1
	v_and_b32_e32 v38, 31, v170
	s_movk_i32 s1, 0x50
	v_mul_lo_u32 v145, v34, s0
	s_addc_u32 s27, s67, 0
	s_add_i32 s0, 0, 0x18a00
	s_movk_i32 s53, 0x3000
	v_readlane_b32 s71, v235, 22
	v_readlane_b32 s92, v234, 17
	s_mov_b32 s17, 0
	v_lshlrev_b32_e32 v43, 2, v67
	v_mov_b32_e32 v37, v1
	v_bfe_u32 v137, v170, 5, 1
	v_mad_u32_u24 v138, v67, s1, 0
	v_cmp_eq_u32_e64 s[6:7], 0, v67
	v_lshl_add_u32 v40, v38, 2, v4
	s_movk_i32 s52, 0x84
	v_or_b32_e32 v141, 8, v139
	v_or_b32_e32 v142, 16, v139
	v_or_b32_e32 v143, 24, v139
	v_mov_b32_e32 v45, v1
	v_lshlrev_b32_e32 v146, 8, v34
	v_lshlrev_b32_e32 v147, 3, v34
	v_lshlrev_b32_e32 v148, 8, v36
	v_lshlrev_b32_e32 v149, 3, v36
	v_add3_u32 v150, s0, v0, v3
	v_add_u32_e32 v48, 0xfe0, v44
	v_mov_b32_e32 v49, v1
	v_lshl_add_u32 v151, v2, 2, 0
	v_lshlrev_b64 v[50:51], 6, v[34:35]
	v_lshlrev_b64 v[52:53], 11, v[34:35]
	v_mad_u64_u32 v[54:55], s[0:1], v34, s53, 0
	s_mov_b64 s[28:29], 0x1420
	v_mov_b32_e32 v57, 1.0
	s_movk_i32 s54, 0x5800
	s_movk_i32 s55, 0x7ff
	s_movk_i32 s56, 0xfff
	s_movk_i32 s57, 0x17ff
	s_movk_i32 s58, 0x37ff
	v_mov_b32_e32 v152, 0x3000000
	s_mov_b32 s59, s71
	v_readlane_b32 s93, v234, 18
	s_mov_b32 s70, s69
	s_branch .LBB0_724
